# attention: hoist all K-fragment LDS reads ahead of QK MFMAs; next-tile LDS staging writes interleaved into PV block (after MFMA 4,7,10,13)
# speedup vs baseline: 1.0133x; 1.0133x over previous
; #define LAS __attribute__((address_space(3)))
; DI unsigned pk2(float lo, float hi) { f32x2 v = {lo, hi}; bf16x2_t b = __builtin_convertvector(v, bf16x2_t); return __builtin_bit_cast(unsigned, b); }
; #define MFMA32(a, b, c) __builtin_amdgcn_mfma_f32_32x32x16_bf16((a), (b), (c), 0, 0, 0)
; template <int NK32>
; DI void attn_tile(const LAS unsigned char* Kb, const LAS unsigned char* Vb, int map, int lane, const bf16x8 (&Q)[4], f32x16 (&O)[4], float& m, float& l) {
;     ...
;     float ps = 0.f;
; #pragma unroll
;     for (int kt = 0; kt < NK32; ++kt)
; #pragma unroll
;         for (int i = 0; i < 16; ++i) { const float p = __builtin_amdgcn_exp2f(S[kt][i] - m); S[kt][i] = p; ps += p; }
;     l += ps;
; #pragma unroll
;     for (int sl = 0; sl < 2 * NK32; ++sl) {
;         const int kt = sl >> 1, r0 = 8 * (sl & 1);
;         v4u pu; pu.x = pk2(S[kt][r0 + 0], S[kt][r0 + 1]); pu.y = pk2(S[kt][r0 + 2], S[kt][r0 + 3]); pu.z = pk2(S[kt][r0 + 4], S[kt][r0 + 5]); pu.w = pk2(S[kt][r0 + 6], S[kt][r0 + 7]);
;         const bf16x8 pf = __builtin_bit_cast(bf16x8, pu);
; #pragma unroll
;         for (int dt = 0; dt < 4; ++dt) {
;             const bf16x8 vf = *(const LAS bf16x8*)(Vb + (dt * 32 + r32) * 144 + sl * 32 + hf * 16);
;             O[dt] = MFMA32(vf, pf, O[dt]);
;         }
;     }
; DI void attn_prompt_item(const __attribute__((address_space(4))) Args& a, LAS unsigned char* lds, int ws_, int b, int h, int qt, float lam, bool dry = false) {
;     ...
;         if (more) {
;             LAS unsigned char* nb = lds + ((kt + 1) & 1) * KV_BYTES;
; #pragma unroll
;             for (int i = 0; i < 2; ++i) { *(LAS v4u*)(nb + kdst[i]) = kx[i]; *(LAS v4u*)(nb + vdst[i]) = vx[i]; }
;         }
;         __syncthreads();
.LBB0_1431:
	s_sub_i32 s11, 0x8c00, s10
	v_add_u32_e32 v210, s11, v132
	v_add_u32_e32 v211, s11, v134
	v_add_u32_e32 v212, s11, v136
	v_add_u32_e32 v213, s11, v138
	v_exp_f32_e32 v155, v80
	v_exp_f32_e32 v156, v81
	v_exp_f32_e32 v165, v82
	v_exp_f32_e32 v166, v83
	v_exp_f32_e32 v168, v84
	v_add_u32_e32 v174, s10, v130
	v_add_f32_e32 v81, 0, v155
	v_exp_f32_e32 v169, v85
	v_add_u32_e32 v175, v174, v139
	v_add_f32_e32 v164, v156, v81
	v_exp_f32_e32 v173, v86
	ds_read_b128 v[80:83], v175 offset:17408
	v_exp_f32_e32 v176, v87
	v_cvt_pk_bf16_f32 v84, v155, v156
	v_add_u32_e32 v155, v174, v137
	ds_read_b128 v[160:163], v155 offset:17408
	v_cvt_pk_bf16_f32 v85, v165, v166
	v_cvt_pk_bf16_f32 v86, v168, v169
	v_cvt_pk_bf16_f32 v87, v173, v176
	ds_read_b128 v[156:159], v175 offset:17440
	v_add_u32_e32 v174, v174, v135
	s_waitcnt lgkmcnt(2)
	v_mfma_f32_32x32x16_bf16 v[48:63], v[80:83], v[84:87], v[48:63]
	v_add_f32_e32 v80, v165, v164
	v_add_f32_e32 v177, v166, v80
	v_exp_f32_e32 v178, v88
	ds_read_b128 v[80:83], v155 offset:17440
	ds_read_b128 v[164:167], v175 offset:26624
	v_exp_f32_e32 v179, v89
	s_waitcnt lgkmcnt(3)
	v_mfma_f32_32x32x16_bf16 v[32:47], v[160:163], v[84:87], v[32:47]
	v_exp_f32_e32 v180, v90
	v_exp_f32_e32 v181, v91
	ds_read_b128 v[88:91], v174 offset:17408
	ds_read_b128 v[160:163], v175 offset:26656
	s_waitcnt lgkmcnt(2)
	v_mfma_f32_32x32x16_bf16 v[16:31], v[164:167], v[84:87], v[16:31]
	v_exp_f32_e32 v92, v92
	v_exp_f32_e32 v93, v93
	v_exp_f32_e32 v94, v94
	ds_read_b128 v[164:167], v174 offset:17440
	s_waitcnt lgkmcnt(2)
	v_mfma_f32_32x32x16_bf16 v[0:15], v[88:91], v[84:87], v[0:15]
	s_waitcnt vmcnt(3)
	ds_write_b128 v210, v[118:121]
	v_exp_f32_e32 v95, v95
	v_cvt_pk_bf16_f32 v84, v178, v179
	v_cvt_pk_bf16_f32 v85, v180, v181
	v_cvt_pk_bf16_f32 v86, v92, v93
	v_cvt_pk_bf16_f32 v87, v94, v95
	v_add_f32_e32 v88, v168, v177
	v_add_f32_e32 v88, v169, v88
	v_mfma_f32_32x32x16_bf16 v[48:63], v[156:159], v[84:87], v[48:63]
	v_exp_f32_e32 v156, v64
	v_exp_f32_e32 v157, v65
	v_exp_f32_e32 v158, v66
	v_exp_f32_e32 v159, v67
	s_waitcnt lgkmcnt(1)
	v_mfma_f32_32x32x16_bf16 v[16:31], v[160:163], v[84:87], v[16:31]
	v_exp_f32_e32 v160, v68
	v_exp_f32_e32 v161, v69
	v_exp_f32_e32 v162, v70
	ds_read_b128 v[64:67], v175 offset:17472
	v_exp_f32_e32 v163, v71
	v_mfma_f32_32x32x16_bf16 v[32:47], v[80:83], v[84:87], v[32:47]
	s_waitcnt vmcnt(2)
	ds_write_b128 v211, v[114:117] offset:17408
	v_add_f32_e32 v88, v173, v88
	v_add_f32_e32 v88, v176, v88
	v_add_f32_e32 v88, v178, v88
	v_cvt_pk_bf16_f32 v68, v156, v157
	v_cvt_pk_bf16_f32 v69, v158, v159
	v_cvt_pk_bf16_f32 v70, v160, v161
	v_cvt_pk_bf16_f32 v71, v162, v163
	s_waitcnt lgkmcnt(1)
	v_mfma_f32_32x32x16_bf16 v[0:15], v[164:167], v[84:87], v[0:15]
	ds_read_b128 v[80:83], v155 offset:17472
	ds_read_b128 v[84:87], v175 offset:17504
	v_exp_f32_e32 v167, v75
	s_waitcnt lgkmcnt(2)
	v_mfma_f32_32x32x16_bf16 v[48:63], v[64:67], v[68:71], v[48:63]
	v_add_f32_e32 v64, v179, v88
	v_add_f32_e32 v64, v180, v64
	v_add_f32_e32 v164, v181, v64
	v_exp_f32_e32 v165, v72
	ds_read_b128 v[64:67], v175 offset:26688
	ds_read_b128 v[88:91], v155 offset:17504
	v_exp_f32_e32 v155, v73
	s_waitcnt lgkmcnt(3)
	v_mfma_f32_32x32x16_bf16 v[32:47], v[80:83], v[68:71], v[32:47]
	s_waitcnt vmcnt(1)
	ds_write_b128 v212, v[126:129]
	v_exp_f32_e32 v166, v74
	ds_read_b128 v[72:75], v174 offset:17472
	ds_read_b128 v[80:83], v175 offset:26720
	s_waitcnt lgkmcnt(1)
	v_mfma_f32_32x32x16_bf16 v[0:15], v[72:75], v[68:71], v[0:15]
	v_add_f32_e32 v74, v92, v164
	v_add_f32_e32 v74, v93, v74
	v_add_f32_e32 v74, v94, v74
	v_add_f32_e32 v74, v95, v74
	v_add_f32_e32 v74, v156, v74
	v_add_f32_e32 v74, v157, v74
	v_add_f32_e32 v74, v158, v74
	v_mfma_f32_32x32x16_bf16 v[16:31], v[64:67], v[68:71], v[16:31]
	v_exp_f32_e32 v76, v76
	v_exp_f32_e32 v77, v77
	ds_read_b128 v[64:67], v174 offset:17504
	v_add_f32_e32 v74, v159, v74
	v_exp_f32_e32 v72, v78
	v_exp_f32_e32 v73, v79
	v_add_f32_e32 v74, v160, v74
	v_add_f32_e32 v74, v161, v74
	v_add_f32_e32 v74, v162, v74
	v_add_f32_e32 v74, v163, v74
	v_cvt_pk_bf16_f32 v68, v165, v155
	v_cvt_pk_bf16_f32 v69, v166, v167
	v_cvt_pk_bf16_f32 v70, v76, v77
	v_cvt_pk_bf16_f32 v71, v72, v73
	v_add_f32_e32 v74, v165, v74
	v_add_f32_e32 v74, v155, v74
	v_mfma_f32_32x32x16_bf16 v[48:63], v[84:87], v[68:71], v[48:63]
	s_waitcnt vmcnt(0)
	ds_write_b128 v213, v[122:125] offset:17408
	v_add_f32_e32 v74, v166, v74
	v_add_f32_e32 v74, v167, v74
	v_add_f32_e32 v74, v76, v74
	v_add_f32_e32 v74, v77, v74
	v_add_f32_e32 v72, v72, v74
	v_add_f32_e32 v72, v73, v72
	v_add_f32_e32 v133, v133, v72
	v_mfma_f32_32x32x16_bf16 v[32:47], v[88:91], v[68:71], v[32:47]
	s_waitcnt lgkmcnt(1)
	v_mfma_f32_32x32x16_bf16 v[16:31], v[80:83], v[68:71], v[16:31]
	s_waitcnt lgkmcnt(0)
	v_mfma_f32_32x32x16_bf16 v[0:15], v[64:67], v[68:71], v[0:15]
	s_add_i32 s9, s9, 1
	s_bitcmp1_b32 s9, 0
	s_cselect_b32 s10, 0x8c00, 0
	v_lshl_add_u64 v[140:141], v[140:141], 0, s[28:29]
	v_lshl_add_u64 v[142:143], v[142:143], 0, s[28:29]
	v_lshl_add_u64 v[144:145], v[144:145], 0, s[30:31]
	s_cmp_eq_u32 s8, s9
	v_lshl_add_u64 v[146:147], v[146:147], 0, s[30:31]
	s_waitcnt lgkmcnt(0)
	s_barrier
	s_cbranch_scc1 .LBB0_1436
	s_branch .LBB0_1433

; #define LAS __attribute__((address_space(3)))
; DI float half_max(float v) { auto rr = __builtin_amdgcn_permlane32_swap(__float_as_uint(v), __float_as_uint(v), false, false); return fmaxf(__uint_as_float(rr[0]), __uint_as_float(rr[1])); }
; #define MFMA32(a, b, c) __builtin_amdgcn_mfma_f32_32x32x16_bf16((a), (b), (c), 0, 0, 0)
; template <int NK32>
; DI void attn_tile(const LAS unsigned char* Kb, const LAS unsigned char* Vb, int map, int lane, const bf16x8 (&Q)[4], f32x16 (&O)[4], float& m, float& l) {
;     ...
;     __builtin_amdgcn_s_setprio(1);
; #pragma unroll
;     for (int kt = 0; kt < NK32; ++kt) {
; #pragma unroll
;         for (int i = 0; i < 16; ++i) S[kt][i] = 0.f;
; #pragma unroll
;         for (int ds = 0; ds < 4; ++ds) {
;             const bf16x8 kf = *(const LAS bf16x8*)(Kb + (kt * 32 + r32) * 272 + map * 128 + ds * 32 + hf * 16);
;             S[kt] = MFMA32(kf, Q[ds], S[kt]);
;         }
;     }
;     __builtin_amdgcn_s_setprio(0);
;     float mx = fmaxf(S[0][0], S[0][1]);
; #pragma unroll
;     for (int kt = 0; kt < NK32; ++kt)
; #pragma unroll
;         for (int i = (kt == 0 ? 2 : 0); i < 16; i += 2) mx = fmaxf(fmaxf(mx, S[kt][i]), S[kt][i + 1]);
;     mx = half_max(mx);
;     if (__any(mx > m + 8.f)) {
;         const float mn = fmaxf(m, mx);
;         const float alpha = __builtin_amdgcn_exp2f(m - mn);
;         m = mn; l *= alpha;
; #pragma unroll
;         for (int dt = 0; dt < 4; ++dt)
; #pragma unroll
;             for (int i = 0; i < 16; ++i) O[dt][i] *= alpha;
;     }
; DI void attn_prompt_item(const __attribute__((address_space(4))) Args& a, LAS unsigned char* lds, int ws_, int b, int h, int qt, float lam, bool dry = false) {
;     ...
;     for (int kt = 0; kt < nt; ++kt) {
;         const bool more = kt + 1 < nt;
;         if (more) {
; #pragma unroll
;             for (int i = 0; i < 2; ++i) { kx[i] = *(const v4u*)(ksrc[i] + (size_t)(kt + 1) * 64 * 1024); vx[i] = *(const v4u*)(vsrc[i] + (kt + 1) * 64); }
;         }
;         const LAS unsigned char* buf = lds + (kt & 1) * KV_BYTES;
;         if (kt < my_nt) attn_tile<2>(buf, buf + KT_BYTES, map, lane, Q, O, m, l);
.LBB0_1433:
	v_lshl_add_u64 v[64:65], s[36:37], 0, v[146:147]
	v_lshl_add_u64 v[66:67], s[36:37], 0, v[142:143]
	global_load_dwordx4 v[118:121], v[64:65], off
	global_load_dwordx4 v[114:117], v[66:67], off
	v_lshl_add_u64 v[64:65], s[36:37], 0, v[144:145]
	v_lshl_add_u64 v[66:67], s[36:37], 0, v[140:141]
	global_load_dwordx4 v[126:129], v[64:65], off
	global_load_dwordx4 v[122:125], v[66:67], off
	s_cmp_ge_u32 s9, s7
	s_cbranch_scc1 .LBB0_1432
	s_bitcmp1_b32 s9, 0
	s_cselect_b32 s10, 0x8c00, 0
	s_add_i32 s10, s10, 0
	s_setprio 1
	s_add_i32 s11, s10, s89
	v_add_u32_e32 v72, s11, v130
	v_add_u32_e32 v73, v72, v153
	v_add_u32_e32 v155, v72, v154
	ds_read_b128 v[64:67], v73
	ds_read_b128 v[68:71], v73 offset:32
	ds_read_b128 v[232:235], v73 offset:64
	ds_read_b128 v[236:239], v73 offset:96
	ds_read_b128 v[240:243], v155
	ds_read_b128 v[244:247], v155 offset:32
	ds_read_b128 v[248:251], v155 offset:64
	ds_read_b128 v[156:159], v155 offset:96
	s_waitcnt vmcnt(7) lgkmcnt(7)
	v_mfma_f32_32x32x16_bf16 v[80:95], v[64:67], v[110:113], v[192:207]
	s_waitcnt vmcnt(6) lgkmcnt(6)
	v_mfma_f32_32x32x16_bf16 v[80:95], v[68:71], v[106:109], v[80:95]
	s_waitcnt vmcnt(5) lgkmcnt(5)
	v_mfma_f32_32x32x16_bf16 v[80:95], v[232:235], v[102:105], v[80:95]
	s_waitcnt vmcnt(4) lgkmcnt(4)
	v_mfma_f32_32x32x16_bf16 v[80:95], v[236:239], v[98:101], v[80:95]
	s_waitcnt lgkmcnt(3)
	v_mfma_f32_32x32x16_bf16 v[64:79], v[240:243], v[110:113], v[192:207]
	s_waitcnt lgkmcnt(2)
	v_mfma_f32_32x32x16_bf16 v[64:79], v[244:247], v[106:109], v[64:79]
	s_waitcnt lgkmcnt(1)
	v_mfma_f32_32x32x16_bf16 v[64:79], v[248:251], v[102:105], v[64:79]
	s_waitcnt lgkmcnt(0)
	v_mfma_f32_32x32x16_bf16 v[64:79], v[156:159], v[98:101], v[64:79]
	s_setprio 0
	s_nop 0
	v_max_f32_e32 v155, v81, v81
	v_max_f32_e32 v156, v80, v80
	v_max_f32_e32 v155, v156, v155
	v_max3_f32 v155, v155, v82, v83
	v_max3_f32 v155, v155, v84, v85
	v_max3_f32 v155, v155, v86, v87
	v_max3_f32 v155, v155, v88, v89
	v_max3_f32 v155, v155, v90, v91
	v_max3_f32 v155, v155, v92, v93
	v_max3_f32 v155, v155, v94, v95
	v_max3_f32 v155, v155, v64, v65
	v_max3_f32 v155, v155, v66, v67
	v_max3_f32 v155, v155, v68, v69
	v_max3_f32 v155, v155, v70, v71
	v_max3_f32 v155, v155, v72, v73
	v_max3_f32 v155, v155, v74, v75
	v_max3_f32 v155, v155, v76, v77
	v_max3_f32 v155, v155, v78, v79
	v_mov_b32_e32 v156, v155
	s_nop 1
	v_permlane32_swap_b32_e32 v155, v156
	v_max_f32_e32 v156, v156, v156
	v_max_f32_e32 v155, v155, v155
	v_max_f32_e32 v155, v155, v156
	v_cmp_gt_f32_e32 vcc, v155, v152
	s_cbranch_vccz .LBB0_1431
	v_max_f32_e32 v155, v155, v209
	v_max_f32_e32 v156, 0, v155
	v_mul_f32_e32 v156, -1.0, v156
	v_exp_f32_e32 v156, v156
	v_sub_f32_e32 v192, v192, v155
	v_mov_b32_e32 v152, 0x41000000
	v_mov_b32_e32 v209, 0
	v_sub_f32_e32 v80, v80, v155
	v_sub_f32_e32 v81, v81, v155
	v_sub_f32_e32 v82, v82, v155
	v_sub_f32_e32 v83, v83, v155
	v_sub_f32_e32 v84, v84, v155
	v_sub_f32_e32 v85, v85, v155
	v_sub_f32_e32 v86, v86, v155
	v_sub_f32_e32 v87, v87, v155
	v_sub_f32_e32 v88, v88, v155
	v_sub_f32_e32 v89, v89, v155
	v_sub_f32_e32 v90, v90, v155
	v_sub_f32_e32 v91, v91, v155
	v_sub_f32_e32 v92, v92, v155
	v_sub_f32_e32 v93, v93, v155
	v_sub_f32_e32 v94, v94, v155
	v_sub_f32_e32 v95, v95, v155
	v_sub_f32_e32 v64, v64, v155
	v_sub_f32_e32 v65, v65, v155
	v_sub_f32_e32 v66, v66, v155
	v_sub_f32_e32 v67, v67, v155
	v_sub_f32_e32 v68, v68, v155
	v_sub_f32_e32 v69, v69, v155
	v_sub_f32_e32 v70, v70, v155
	v_sub_f32_e32 v71, v71, v155
	v_sub_f32_e32 v72, v72, v155
	v_sub_f32_e32 v73, v73, v155
	v_sub_f32_e32 v74, v74, v155
	v_sub_f32_e32 v75, v75, v155
	v_sub_f32_e32 v76, v76, v155
	v_sub_f32_e32 v77, v77, v155
	v_sub_f32_e32 v78, v78, v155
	v_sub_f32_e32 v79, v79, v155
	v_mov_b32_e32 v193, v192
	v_mov_b32_e32 v194, v192
	v_mov_b32_e32 v195, v192
	v_mov_b32_e32 v196, v192
	v_mov_b32_e32 v197, v192
	v_mov_b32_e32 v198, v192
	v_mov_b32_e32 v199, v192
	v_mov_b32_e32 v200, v192
	v_mov_b32_e32 v201, v192
	v_mov_b32_e32 v202, v192
	v_mov_b32_e32 v203, v192
	v_mov_b32_e32 v204, v192
	v_mov_b32_e32 v205, v192
	v_mov_b32_e32 v206, v192
	v_mov_b32_e32 v207, v192
	v_mul_f32_e32 v133, v133, v156
	v_pk_mul_f32 v[62:63], v[62:63], v[156:157] op_sel_hi:[1,0]
	v_pk_mul_f32 v[60:61], v[60:61], v[156:157] op_sel_hi:[1,0]
	v_pk_mul_f32 v[58:59], v[58:59], v[156:157] op_sel_hi:[1,0]
	v_pk_mul_f32 v[56:57], v[56:57], v[156:157] op_sel_hi:[1,0]
	v_pk_mul_f32 v[54:55], v[54:55], v[156:157] op_sel_hi:[1,0]
	v_pk_mul_f32 v[52:53], v[52:53], v[156:157] op_sel_hi:[1,0]
	v_pk_mul_f32 v[50:51], v[50:51], v[156:157] op_sel_hi:[1,0]
	v_pk_mul_f32 v[48:49], v[48:49], v[156:157] op_sel_hi:[1,0]
	v_pk_mul_f32 v[46:47], v[46:47], v[156:157] op_sel_hi:[1,0]
	v_pk_mul_f32 v[44:45], v[44:45], v[156:157] op_sel_hi:[1,0]
	v_pk_mul_f32 v[42:43], v[42:43], v[156:157] op_sel_hi:[1,0]
	v_pk_mul_f32 v[40:41], v[40:41], v[156:157] op_sel_hi:[1,0]
	v_pk_mul_f32 v[38:39], v[38:39], v[156:157] op_sel_hi:[1,0]
	v_pk_mul_f32 v[36:37], v[36:37], v[156:157] op_sel_hi:[1,0]
	v_pk_mul_f32 v[34:35], v[34:35], v[156:157] op_sel_hi:[1,0]
	v_pk_mul_f32 v[32:33], v[32:33], v[156:157] op_sel_hi:[1,0]
	v_pk_mul_f32 v[30:31], v[30:31], v[156:157] op_sel_hi:[1,0]
	v_pk_mul_f32 v[28:29], v[28:29], v[156:157] op_sel_hi:[1,0]
	v_pk_mul_f32 v[26:27], v[26:27], v[156:157] op_sel_hi:[1,0]
	v_pk_mul_f32 v[24:25], v[24:25], v[156:157] op_sel_hi:[1,0]
	v_pk_mul_f32 v[22:23], v[22:23], v[156:157] op_sel_hi:[1,0]
	v_pk_mul_f32 v[20:21], v[20:21], v[156:157] op_sel_hi:[1,0]
	v_pk_mul_f32 v[18:19], v[18:19], v[156:157] op_sel_hi:[1,0]
	v_pk_mul_f32 v[16:17], v[16:17], v[156:157] op_sel_hi:[1,0]
	v_pk_mul_f32 v[14:15], v[14:15], v[156:157] op_sel_hi:[1,0]
	v_pk_mul_f32 v[12:13], v[12:13], v[156:157] op_sel_hi:[1,0]
	v_pk_mul_f32 v[10:11], v[10:11], v[156:157] op_sel_hi:[1,0]
	v_pk_mul_f32 v[8:9], v[8:9], v[156:157] op_sel_hi:[1,0]
	v_pk_mul_f32 v[6:7], v[6:7], v[156:157] op_sel_hi:[1,0]
	v_pk_mul_f32 v[4:5], v[4:5], v[156:157] op_sel_hi:[1,0]
	v_pk_mul_f32 v[2:3], v[2:3], v[156:157] op_sel_hi:[1,0]
	v_pk_mul_f32 v[0:1], v[0:1], v[156:157] op_sel_hi:[1,0]
	s_branch .LBB0_1431
